# static priority raise (s_setprio 1) for waves 4-7 during the wave-task token-mixing phases, reset before the next GEMM phase
# baseline (speedup 1.0000x reference)
; #define LAS __attribute__((address_space(3)))
; #define AIN(k) ((const float*)argp(lds, (k)))
; __global__ void __launch_bounds__(NWAVES * 64, 2) fwd_kernel(KArgs a) {
;     ...
;             PHASE_PTRS();
;     ...
;             { const float* dw = AIN(6) + l * 31 * 256; const int tl = wave * 64 + ln;
;               for (int i = tl; i < 31 * 64; i += NWAVES * 64) ((LAS f32x4*)lds)[i] = ((const f32x4*)dw)[i];
;               __syncthreads(); }
.LBB0_322:
	s_or_b64 exec, exec, s[0:1]
	v_readlane_b32 s0, v215, 32
	v_readlane_b32 s1, v215, 33
	s_xor_b64 s[0:1], s[0:1], -1
	v_writelane_b32 v215, s0, 43
	s_waitcnt lgkmcnt(0)
	s_barrier
	s_cmp_ge_u32 s33, 0x10000
	s_cbranch_scc0 .Lprio_pb_skip
	s_setprio 1
.Lprio_pb_skip:
	v_writelane_b32 v215, s1, 44
	s_nop 0
	v_readlane_b32 s0, v215, 0
	v_readlane_b32 s54, v254, 6
	s_nop 0
	v_mov_b32_e32 v0, s0
	ds_read_b64 v[0:1], v0
	s_mov_b32 s0, s96
	v_mbcnt_lo_u32_b32 v2, -1, 0
	v_mbcnt_hi_u32_b32 v2, -1, v2
	s_waitcnt lgkmcnt(0)
	v_readfirstlane_b32 s42, v0
	v_mov_b32_e32 v0, s0
	v_readfirstlane_b32 s43, v1
	ds_read_b64 v[0:1], v0
	v_readlane_b32 s0, v215, 17
	s_waitcnt lgkmcnt(0)
	s_nop 0
	v_mov_b32_e32 v0, s0
	ds_read_b64 v[0:1], v0
	v_readlane_b32 s0, v254, 45
	s_waitcnt lgkmcnt(0)
	v_readfirstlane_b32 s3, v0
	v_add_u32_e32 v0, s0, v2
	s_movk_i32 s0, 0x7c0
	v_readfirstlane_b32 s2, v1
	v_cmp_gt_i32_e32 vcc, s0, v0
	s_and_saveexec_b64 s[0:1], vcc
	s_cbranch_execz .LBB0_325
	v_readlane_b32 s4, v254, 46
	v_ashrrev_i32_e32 v1, 31, v0
	s_nop 0
	v_add_u32_e32 v3, s4, v2
	v_readlane_b32 s4, v215, 40
	v_readlane_b32 s5, v215, 41
	s_mul_hi_u32 s5, s4, 0x7c00
	s_mulk_i32 s4, 0x7c00
	s_add_u32 s4, s3, s4
	s_addc_u32 s5, s2, s5
	v_readlane_b32 s2, v254, 47
	v_lshl_add_u64 v[0:1], v[0:1], 4, s[4:5]
	s_nop 0
	v_lshl_add_u32 v2, v2, 4, s2
	s_mov_b64 s[2:3], 0

; __device__ __forceinline__ unsigned xb_add(unsigned* p, unsigned v) { return __hip_atomic_fetch_add(p, v, __ATOMIC_RELAXED, __HIP_MEMORY_SCOPE_AGENT); }
; __device__ __forceinline__ void xcd_barrier(const XcdBarrier& b) {
;     asm volatile("s_waitcnt vmcnt(0)" ::: "memory");
;     __syncthreads();
;     if (threadIdx.x == 0) {
;         unsigned* bar = b.bar;
;         unsigned bx = (unsigned)__builtin_amdgcn_readfirstlane((int)b.x); asm volatile("" : "+s"(bx));
;         __builtin_amdgcn_s_waitcnt(0);
;         unsigned nloc = b.st[0], nx = b.st[1];
;         if (nloc == 0u) { xcd_barrier_complete(bar, bx, nloc, nx); b.st[0] = nloc; b.st[1] = nx; }
;         const unsigned old = xb_add(&bar[XB_XSUB(bx)], 1u);
.LBB0_552:
	s_setprio 0
	s_waitcnt vmcnt(0)
	s_barrier
	s_mov_b64 s[0:1], exec
	v_readlane_b32 s2, v254, 4
	v_readlane_b32 s3, v254, 5
	s_and_b64 s[2:3], s[0:1], s[2:3]
	s_mov_b64 exec, s[2:3]
	s_cbranch_execz .LBB0_604
	v_readlane_b32 s2, v215, 15
	v_readlane_b32 s8, v254, 3
	s_waitcnt vmcnt(0) expcnt(0) lgkmcnt(0)
	v_mov_b32_e32 v0, s2
	ds_read_b32 v2, v0
	v_readlane_b32 s2, v215, 16
	s_waitcnt lgkmcnt(0)
	v_cmp_ne_u32_e32 vcc, 0, v2
	v_mov_b32_e32 v0, s2
	ds_read_b32 v0, v0
	s_cbranch_vccnz .LBB0_568
	s_mov_b32 s9, 1
	s_branch .LBB0_556
